# stack: seam weight conversion + weight-copy pipeline fix + attention bias batching/V hoist/softmax-PV interleave + write-through GEMM epilogue stores
# speedup vs baseline: 1.0100x; 1.0016x over previous
; __global__ void __launch_bounds__(NWAVES * 64, 2) hybrid_fwd(Args args) {
;     ...
;         {
;             int it = gw; f32x4 va[16]; float ga[16]; TItem d0;
;             if (it < DEPTH * I_L) { d0 = decode(it); titem_load(d0, va, ga, lane); }
;             while (it < DEPTH * I_L) {
;                 const int itn = it + NGW; f32x4 vb[16]; float gb[16]; TItem d1;
;                 if (itn < DEPTH * I_L) { d1 = decode(itn); titem_load(d1, vb, gb, lane); }
.LBB0_56:
	s_waitcnt vmcnt(0) lgkmcnt(0)
	s_add_u32 s27, s24, 0x10200000
	s_addc_u32 s33, s25, 0
	s_add_u32 s46, s24, 0x8200000
	s_addc_u32 s47, s25, 0
	s_add_u32 s48, s24, 0x6200000
	s_addc_u32 s49, s25, 0
	v_lshrrev_b32_e32 v66, 1, v169
	s_add_u32 s50, s24, 0x200000
	v_and_b32_e32 v179, 24, v66
	s_addc_u32 s51, s25, 0
	s_movk_i32 s52, 0xfff
	v_mov_b32_e32 v131, 0
	s_movk_i32 s53, 0x1000
	s_movk_i32 s54, 0x13ff
	s_movk_i32 s55, 0xffe
	s_movk_i32 s56, 0xffd
	v_mov_b32_e32 v180, 0x7ffff000
	v_mov_b32_e32 v181, 0x7fffec00
	v_mov_b32_e32 v182, 0x80
	s_mov_b32 s57, s22
	s_branch .LBB0_58

; __device__ __forceinline__ void titem_load(const TItem& d, f32x4 (&v)[16], float (&gg)[16], int lane) {
; #pragma unroll
;     for (int i = 0; i < 16; ++i) { const int kk = 32 * (i >> 3) + 8 * (lane >> 4) + (i & 7); v[i] = *(const f32x4*)(d.src + (size_t)kk * d.N + (lane & 15) * 4); gg[i] = d.g ? d.g[kk] : 1.f; }
; }
.LBB0_72:
	v_mov_b32_e32 v132, 1.0
	v_mov_b32_e32 v71, v131
	v_mov_b32_e32 v133, v132

; __device__ __forceinline__ void titem_load(const TItem& d, f32x4 (&v)[16], float (&gg)[16], int lane) {
; #pragma unroll
;     for (int i = 0; i < 16; ++i) { const int kk = 32 * (i >> 3) + 8 * (lane >> 4) + (i & 7); v[i] = *(const f32x4*)(d.src + (size_t)kk * d.N + (lane & 15) * 4); gg[i] = d.g ? d.g[kk] : 1.f; }
; }
.LBB0_75:
	v_mov_b32_e32 v134, 1.0
	v_mov_b32_e32 v79, v131
	v_mov_b32_e32 v135, v134

; __device__ __forceinline__ void titem_load(const TItem& d, f32x4 (&v)[16], float (&gg)[16], int lane) {
; #pragma unroll
;     for (int i = 0; i < 16; ++i) { const int kk = 32 * (i >> 3) + 8 * (lane >> 4) + (i & 7); v[i] = *(const f32x4*)(d.src + (size_t)kk * d.N + (lane & 15) * 4); gg[i] = d.g ? d.g[kk] : 1.f; }
; }
.LBB0_78:
	v_mov_b32_e32 v136, 1.0
	v_mov_b32_e32 v87, v131
	v_mov_b32_e32 v137, v136

; __device__ __forceinline__ void titem_load(const TItem& d, f32x4 (&v)[16], float (&gg)[16], int lane) {
; #pragma unroll
;     for (int i = 0; i < 16; ++i) { const int kk = 32 * (i >> 3) + 8 * (lane >> 4) + (i & 7); v[i] = *(const f32x4*)(d.src + (size_t)kk * d.N + (lane & 15) * 4); gg[i] = d.g ? d.g[kk] : 1.f; }
; }
.LBB0_81:
	v_mov_b32_e32 v95, v131
	v_mov_b32_e32 v183, 1.0
	v_mov_b32_e32 v184, 1.0

; __device__ __forceinline__ void titem_load(const TItem& d, f32x4 (&v)[16], float (&gg)[16], int lane) {
; #pragma unroll
;     for (int i = 0; i < 16; ++i) { const int kk = 32 * (i >> 3) + 8 * (lane >> 4) + (i & 7); v[i] = *(const f32x4*)(d.src + (size_t)kk * d.N + (lane & 15) * 4); gg[i] = d.g ? d.g[kk] : 1.f; }
; }
.LBB0_84:
	v_mov_b32_e32 v138, 1.0
	v_mov_b32_e32 v103, v131
	v_mov_b32_e32 v139, v138

; __device__ __forceinline__ void titem_load(const TItem& d, f32x4 (&v)[16], float (&gg)[16], int lane) {
; #pragma unroll
;     for (int i = 0; i < 16; ++i) { const int kk = 32 * (i >> 3) + 8 * (lane >> 4) + (i & 7); v[i] = *(const f32x4*)(d.src + (size_t)kk * d.N + (lane & 15) * 4); gg[i] = d.g ? d.g[kk] : 1.f; }
; }
.LBB0_87:
	v_mov_b32_e32 v140, 1.0
	v_mov_b32_e32 v111, v131
	v_mov_b32_e32 v141, v140

; __device__ __forceinline__ void titem_load(const TItem& d, f32x4 (&v)[16], float (&gg)[16], int lane) {
; #pragma unroll
;     for (int i = 0; i < 16; ++i) { const int kk = 32 * (i >> 3) + 8 * (lane >> 4) + (i & 7); v[i] = *(const f32x4*)(d.src + (size_t)kk * d.N + (lane & 15) * 4); gg[i] = d.g ? d.g[kk] : 1.f; }
; }
.LBB0_90:
	v_mov_b32_e32 v142, 1.0
	v_mov_b32_e32 v119, v131
	v_mov_b32_e32 v143, v142

; __device__ __forceinline__ void titem_load(const TItem& d, f32x4 (&v)[16], float (&gg)[16], int lane) {
; #pragma unroll
;     for (int i = 0; i < 16; ++i) { const int kk = 32 * (i >> 3) + 8 * (lane >> 4) + (i & 7); v[i] = *(const f32x4*)(d.src + (size_t)kk * d.N + (lane & 15) * 4); gg[i] = d.g ? d.g[kk] : 1.f; }
; }
.LBB0_93:
	v_mov_b32_e32 v127, v131
	v_mov_b32_e32 v185, 1.0
	v_mov_b32_e32 v186, 1.0

; __host__ __device__ __forceinline__ int blk_off(int r, int c) { const int rr = r & 127; return (r >> 7) * 8192 + (((rr >> 4) * 2 + (c >> 5)) * 512) + (rr & 15) * 32 + (c & 31); }
; __device__ __forceinline__ unsigned cvt_pk_bf16(float lo, float hi) { unsigned r; asm volatile("v_cvt_pk_bf16_f32 %0, %1, %2" : "=v"(r) : "v"(lo), "v"(hi)); return r; }
; __device__ __forceinline__ void titem_process(const TItem& d, const f32x4 (&v)[16], const float (&gg)[16], int lane) {
;     const int n0 = d.perm >> 1;
; #pragma unroll
;     for (int j = 0; j < 4; ++j) { const int n = n0 + 4 * (lane & 15) + j, nr = (d.perm & 1) ? win_row(n) : n;
;         const int w32 = nr & 31, nrs = (nr & 255 & ~31) + 16 * ((w32 >> 2) & 1) + 4 * (w32 >> 3) + (w32 & 3);
;         bf16* rowp = d.dst + (size_t)(nr >> 8) * (d.K >> 6) * (256 * 64);
; #pragma unroll
;         for (int h = 0; h < 2; ++h) { v4u o;
;             o.x = pg8::cvt_pk_bf16(v[8 * h + 0][j] * gg[8 * h + 0], v[8 * h + 1][j] * gg[8 * h + 1]); o.y = pg8::cvt_pk_bf16(v[8 * h + 2][j] * gg[8 * h + 2], v[8 * h + 3][j] * gg[8 * h + 3]);
;             o.z = pg8::cvt_pk_bf16(v[8 * h + 4][j] * gg[8 * h + 4], v[8 * h + 5][j] * gg[8 * h + 5]); o.w = pg8::cvt_pk_bf16(v[8 * h + 6][j] * gg[8 * h + 6], v[8 * h + 7][j] * gg[8 * h + 7]);
;             *(v4u*)(rowp + pg8::blk_off(nrs, 8 * (lane >> 4) + 32 * h)) = o; } }
.LBB0_101:
	v_and_b32_e32 v188, 0x60, v130
	v_lshlrev_b32_e32 v189, 2, v130
	s_ashr_i32 s4, s3, 6
	v_and_or_b32 v194, v189, 16, v188
	v_lshrrev_b32_e32 v188, 1, v130
	v_and_b32_e32 v189, 3, v130
	v_ashrrev_i32_e32 v191, 8, v130
	s_ashr_i32 s5, s4, 31
	v_and_or_b32 v190, v188, 12, v189
	v_ashrrev_i32_e32 v188, 31, v191
	s_lshl_b64 s[36:37], s[4:5], 15
	v_lshlrev_b32_e32 v130, 6, v130
	v_mul_lo_u32 v195, s36, v188
	s_lshr_b64 s[4:5], s[4:5], 17
	v_mov_b64_e32 v[188:189], s[0:1]
	v_and_b32_e32 v130, 0x2000, v130
	v_mul_i32_i24_e32 v196, s4, v191
	v_mad_u64_u32 v[192:193], s[4:5], s36, v191, v[188:189]
	v_lshl_or_b32 v130, v190, 5, v130
	v_mul_f32_e32 v188, v162, v2
	v_mul_f32_e32 v189, v161, v6
	v_lshlrev_b32_e32 v194, 6, v194
	v_cvt_pk_bf16_f32 v188, v188, v189
	v_mul_f32_e32 v189, v164, v10
	v_mul_f32_e32 v190, v163, v14
	v_or3_b32 v130, v130, v194, v179
	v_add3_u32 v193, v196, v193, v195
	v_cvt_pk_bf16_f32 v189, v189, v190
	v_mul_f32_e32 v190, v166, v18
	v_mul_f32_e32 v191, v165, v22
	v_lshlrev_b32_e32 v130, 1, v130
	v_cvt_pk_bf16_f32 v190, v190, v191
	v_mul_f32_e32 v191, v168, v26
	v_lshl_add_u64 v[192:193], v[192:193], 0, v[130:131]
	v_mul_f32_e32 v195, v167, v30
	v_cvt_pk_bf16_f32 v191, v191, v195
	global_store_dwordx4 v[192:193], v[188:191], off
	v_mul_f32_e32 v130, v171, v34
	s_andn2_b64 vcc, exec, s[38:39]
	v_mul_f32_e32 v188, v170, v38
	v_cvt_pk_bf16_f32 v188, v130, v188
	v_mul_f32_e32 v130, v173, v42
	v_mul_f32_e32 v189, v172, v46
	v_cvt_pk_bf16_f32 v189, v130, v189
	v_mul_f32_e32 v130, v175, v50
	v_mul_f32_e32 v190, v174, v54
	v_cvt_pk_bf16_f32 v190, v130, v190
	v_mul_f32_e32 v130, v178, v58
	v_mul_f32_e32 v191, v176, v62
	v_cvt_pk_bf16_f32 v191, v130, v191
	v_cndmask_b32_e64 v130, 0, 1, s[38:39]
	v_cmp_ne_u32_e64 s[4:5], 1, v130
	v_add_u32_e32 v130, 1, v187
	global_store_dwordx4 v[192:193], v[188:191], off offset:1024
	s_cbranch_vccnz .LBB0_107
	v_cmp_gt_i32_e32 vcc, s52, v187
	s_and_saveexec_b64 s[38:39], vcc
	s_xor_b64 s[38:39], exec, s[38:39]
	v_lshlrev_b32_e32 v188, 2, v130
	v_lshrrev_b32_e32 v189, 1, v130
	v_and_b32_e32 v188, 0x80, v188
	v_and_b32_e32 v189, 0x60, v189
	v_and_b32_e32 v130, 0xffffff1f, v130
	v_or3_b32 v130, v188, v130, v189
	s_andn2_saveexec_b64 s[38:39], s[38:39]
	v_cmp_lt_u32_e32 vcc, s54, v130
	s_nop 1
	v_cndmask_b32_e32 v188, v180, v181, vcc
	v_add_lshl_u32 v188, v188, v130, 1
	v_and_b32_e32 v188, 0xffffff00, v188
	v_cndmask_b32_e32 v189, 0, v182, vcc
	v_and_b32_e32 v130, 0x7f, v130
	v_or3_b32 v130, v188, v189, v130
	v_add_u32_e32 v130, 0x1000, v130
	s_or_b64 exec, exec, s[38:39]

; __host__ __device__ __forceinline__ int blk_off(int r, int c) { const int rr = r & 127; return (r >> 7) * 8192 + (((rr >> 4) * 2 + (c >> 5)) * 512) + (rr & 15) * 32 + (c & 31); }
; __device__ __forceinline__ unsigned cvt_pk_bf16(float lo, float hi) { unsigned r; asm volatile("v_cvt_pk_bf16_f32 %0, %1, %2" : "=v"(r) : "v"(lo), "v"(hi)); return r; }
; __device__ __forceinline__ void titem_process(const TItem& d, const f32x4 (&v)[16], const float (&gg)[16], int lane) {
;     const int n0 = d.perm >> 1;
; #pragma unroll
;     for (int j = 0; j < 4; ++j) { const int n = n0 + 4 * (lane & 15) + j, nr = (d.perm & 1) ? win_row(n) : n;
;         const int w32 = nr & 31, nrs = (nr & 255 & ~31) + 16 * ((w32 >> 2) & 1) + 4 * (w32 >> 3) + (w32 & 3);
;         bf16* rowp = d.dst + (size_t)(nr >> 8) * (d.K >> 6) * (256 * 64);
; #pragma unroll
;         for (int h = 0; h < 2; ++h) { v4u o;
;             o.x = pg8::cvt_pk_bf16(v[8 * h + 0][j] * gg[8 * h + 0], v[8 * h + 1][j] * gg[8 * h + 1]); o.y = pg8::cvt_pk_bf16(v[8 * h + 2][j] * gg[8 * h + 2], v[8 * h + 3][j] * gg[8 * h + 3]);
;             o.z = pg8::cvt_pk_bf16(v[8 * h + 4][j] * gg[8 * h + 4], v[8 * h + 5][j] * gg[8 * h + 5]); o.w = pg8::cvt_pk_bf16(v[8 * h + 6][j] * gg[8 * h + 6], v[8 * h + 7][j] * gg[8 * h + 7]);
;             *(v4u*)(rowp + pg8::blk_off(nrs, 8 * (lane >> 4) + 32 * h)) = o; } }
; __global__ void __launch_bounds__(NWAVES * 64, 2) hybrid_fwd(Args args) {
;     ...
;                 if (itn < DEPTH * I_L) {
; #pragma unroll
;                     for (int i = 0; i < 16; ++i) { va[i] = vb[i]; ga[i] = gb[i]; }
;                     d0 = d1; }
;                 it = itn;
.LBB0_119:
	v_and_b32_e32 v187, 0x60, v130
	v_lshlrev_b32_e32 v188, 2, v130
	v_and_or_b32 v187, v188, 16, v187
	v_lshrrev_b32_e32 v188, 1, v130
	v_and_b32_e32 v189, 3, v130
	v_ashrrev_i32_e32 v191, 8, v130
	v_and_or_b32 v190, v188, 12, v189
	v_ashrrev_i32_e32 v188, 31, v191
	v_lshlrev_b32_e32 v130, 6, v130
	v_mul_lo_u32 v194, s36, v188
	v_mov_b64_e32 v[188:189], s[0:1]
	v_and_b32_e32 v130, 0x2000, v130
	v_mad_u64_u32 v[192:193], s[4:5], s36, v191, v[188:189]
	v_lshl_or_b32 v130, v190, 5, v130
	v_mul_f32_e32 v188, v162, v5
	v_mul_f32_e32 v189, v161, v9
	v_lshlrev_b32_e32 v187, 6, v187
	v_mul_i32_i24_e32 v195, s37, v191
	v_cvt_pk_bf16_f32 v188, v188, v189
	v_mul_f32_e32 v189, v164, v13
	v_mul_f32_e32 v190, v163, v17
	v_or3_b32 v130, v130, v187, v179
	v_add3_u32 v193, v195, v193, v194
	v_cvt_pk_bf16_f32 v189, v189, v190
	v_mul_f32_e32 v190, v166, v21
	v_mul_f32_e32 v191, v165, v25
	v_lshlrev_b32_e32 v130, 1, v130
	v_cvt_pk_bf16_f32 v190, v190, v191
	v_mul_f32_e32 v191, v168, v29
	v_lshl_add_u64 v[192:193], v[192:193], 0, v[130:131]
	v_mul_f32_e32 v130, v171, v37
	v_mul_f32_e32 v187, v170, v41
	v_mul_f32_e32 v194, v167, v33
	v_cvt_pk_bf16_f32 v191, v191, v194
	global_store_dwordx4 v[192:193], v[188:191], off
	s_andn2_b64 vcc, exec, s[30:31]
	s_nop 0
	v_cvt_pk_bf16_f32 v188, v130, v187
	v_mul_f32_e32 v130, v173, v45
	v_mul_f32_e32 v187, v172, v49
	v_cvt_pk_bf16_f32 v189, v130, v187
	v_mul_f32_e32 v130, v175, v53
	v_mul_f32_e32 v187, v174, v57
	v_cvt_pk_bf16_f32 v190, v130, v187
	v_mul_f32_e32 v130, v178, v61
	v_mul_f32_e32 v187, v176, v65
	v_cvt_pk_bf16_f32 v191, v130, v187
	global_store_dwordx4 v[192:193], v[188:191], off offset:1024
	s_cbranch_vccnz .LBB0_57
	s_waitcnt vmcnt(8)
	v_mov_b64_e32 v[62:63], v[126:127]
	v_mov_b64_e32 v[58:59], v[118:119]
	v_mov_b64_e32 v[54:55], v[122:123]
	v_mov_b64_e32 v[50:51], v[110:111]
	v_mov_b64_e32 v[46:47], v[114:115]
	v_mov_b64_e32 v[42:43], v[102:103]
	v_mov_b64_e32 v[38:39], v[106:107]
	v_mov_b64_e32 v[34:35], v[94:95]
	v_mov_b64_e32 v[30:31], v[98:99]
	v_mov_b64_e32 v[26:27], v[86:87]
	v_mov_b64_e32 v[22:23], v[90:91]
	v_mov_b64_e32 v[18:19], v[78:79]
	v_mov_b64_e32 v[14:15], v[82:83]
	v_mov_b64_e32 v[10:11], v[70:71]
	v_mov_b64_e32 v[6:7], v[74:75]
	v_mov_b64_e32 v[2:3], v[66:67]
	v_mov_b64_e32 v[64:65], v[128:129]
	v_mov_b64_e32 v[60:61], v[120:121]
	v_mov_b64_e32 v[56:57], v[124:125]
	v_mov_b64_e32 v[52:53], v[112:113]
	v_mov_b64_e32 v[48:49], v[116:117]
	v_mov_b64_e32 v[44:45], v[104:105]
	v_mov_b64_e32 v[40:41], v[108:109]
	v_mov_b64_e32 v[36:37], v[96:97]
	v_mov_b64_e32 v[32:33], v[100:101]
	v_mov_b64_e32 v[28:29], v[88:89]
	v_mov_b64_e32 v[24:25], v[92:93]
	v_mov_b64_e32 v[20:21], v[80:81]
	v_mov_b64_e32 v[16:17], v[84:85]
	v_mov_b64_e32 v[12:13], v[72:73]
	v_mov_b64_e32 v[8:9], v[76:77]
	v_mov_b64_e32 v[4:5], v[68:69]
	s_mov_b64 s[0:1], s[34:35]
	s_mov_b32 s3, s58
	s_mov_b32 s23, s40
	v_mov_b32_e32 v162, v132
	v_mov_b32_e32 v161, v133
	v_mov_b32_e32 v164, v134
	v_mov_b32_e32 v163, v135
	v_mov_b32_e32 v166, v136
	v_mov_b32_e32 v165, v137
	v_mov_b32_e32 v168, v183
	v_mov_b32_e32 v167, v184
	v_mov_b32_e32 v171, v138
	v_mov_b32_e32 v170, v139
	v_mov_b32_e32 v173, v140
	v_mov_b32_e32 v172, v141
	v_mov_b32_e32 v175, v142
	v_mov_b32_e32 v174, v143
	v_mov_b32_e32 v178, v185
	v_mov_b32_e32 v176, v186
	s_branch .LBB0_57
